# v38 plus next-task k_k/k_a prefetch ahead of the stage-4 stores (loop-top wait no longer drains the stores) plus deeper modulation GEMV loads
# baseline (speedup 1.0000x reference)
; #define LAS __attribute__((address_space(3)))
; __device__ __forceinline__ f32x4 zero4v() { f32x4 z = (f32x4){0.f, 0.f, 0.f, 0.f}; asm volatile("" : "+v"(z)); return z; }
; __device__ __forceinline__ void rwkvA_phase(const Frame& F, int l) {
;     unsigned char* ws = F.ws;
;     const float* Rf = (const float*)(ws + WS_RF); const float* Kf = (const float*)(ws + WS_KF); const float* Vf = (const float*)(ws + WS_VF);
;     float* MN = (float*)(ws + WS_MN); bf16_t* RY = (bf16_t*)(ws + WS_RY);
;     const int qi = F.lane & 15, g = F.lane >> 4, tr = F.wave >> 1, tcb = (F.wave & 1) * 2;
;     LAS unsigned char* L = F.lds;
;     LAS float* Af = (LAS float*)(L + O_AF); LAS float* Tf = (LAS float*)(L + O_TF); LAS float* tot = (LAS float*)(L + O_TOT); LAS float* gL = (LAS float*)(L + O_GL);
;     float pk_[8], pv_[8], pr_[8], pza_[8], pzw_[8];
;     ...
;     constexpr int RA_NONB = 256 - RB_BLOCKS, RA_NT0 = CH_NTASK - RB_BLOCKS * RA_BTASKS;
;     static_assert(RA_NT0 % RA_NONB == 0, "chunk task split");
;     const bool split = (F.nb == 256);
;     int t0 = F.bid, tstride = F.nb, tend = CH_NTASK;
;     if (split) { if (F.bid < RB_BLOCKS) { t0 = RA_NT0 + F.bid; tstride = RB_BLOCKS; } else { t0 = F.bid - RB_BLOCKS; tstride = RA_NONB; tend = RA_NT0; } }
;     if (split && F.bid < RB_BLOCKS) { mla_unit(F, F.bid & 7, (F.bid >> 3) * 256, 0, MLA_SPLIT, 1, F.bid); __syncthreads(); }
;     if (t0 < tend) RA_LOAD(t0);
;     for (int task = t0; task < tend; task += tstride) {
;         const f32x4 z4 = zero4v();
;         const int hd = task / CH_NCH, c = task - hd * CH_NCH, head = hd >> 1, dir = hd & 1;
;         const int ch = head * 64 + F.lane;
;         const float kkc = F.in[I_KK][(size_t)l * AW + ch], kac = F.in[I_KA][(size_t)l * AW + ch];
.LBB0_747:
	s_andn2_b64 vcc, exec, s[0:1]
	s_cbranch_vccnz .LBB0_784
	v_writelane_b32 v255, s34, 12
	s_lshl_b32 s0, s92, 10
	s_mov_b32 s1, s73
	v_writelane_b32 v255, s35, 13
	v_writelane_b32 v255, s0, 14
	v_ashrrev_i32_e32 v36, 4, v198
	v_and_b32_e32 v56, 15, v198
	v_writelane_b32 v255, s1, 15
	s_add_u32 s0, s80, 0x577a4000
	v_writelane_b32 v255, s0, 16
	s_addc_u32 s0, s81, 0
	v_writelane_b32 v255, s0, 17
	s_lshl_b32 s0, s82, 1
	s_ashr_i32 s4, s82, 1
	s_and_b32 s34, s0, 2
	s_add_u32 s0, s80, 0x3db24000
	v_writelane_b32 v255, s0, 18
	s_addc_u32 s0, s81, 0
	v_writelane_b32 v255, s0, 19
	s_add_u32 s0, s80, 0x41d24000
	v_writelane_b32 v255, s0, 20
	s_addc_u32 s0, s81, 0
	v_writelane_b32 v255, s0, 21
	s_lshl_b32 s0, s4, 4
	v_lshlrev_b32_e32 v76, 2, v36
	s_movk_i32 s1, 0x240
	v_or_b32_e32 v0, s0, v56
	v_add_u32_e32 v77, s0, v76
	s_mul_i32 s0, s4, 0x900
	v_mul_lo_u32 v1, v36, s1
	v_lshlrev_b32_e32 v37, 2, v56
	v_readlane_b32 s8, v254, 27
	v_and_b32_e32 v75, -16, v198
	v_add_u32_e32 v1, s0, v1
	v_lshlrev_b32_e32 v2, 1, v56
	s_add_i32 s0, 0, 0x12000
	v_readlane_b32 s1, v254, 28
	s_lshl_b32 s36, s34, 4
	v_add_u32_e32 v3, s8, v37
	v_add3_u32 v79, 0, v2, v1
	v_add3_u32 v80, s0, v2, v1
	v_add3_u32 v81, s1, v2, v1
	v_lshlrev_b32_e32 v1, 2, v75
	v_readlane_b32 s9, v254, 29
	v_or_b32_e32 v45, s36, v56
	v_add_u32_e32 v83, v3, v1
	v_add_u32_e32 v82, s9, v1
	v_lshlrev_b32_e32 v2, 3, v36
	v_bfe_u32 v1, v198, 2, 2
	v_lshl_or_b32 v58, v77, 6, v45
	v_mul_lo_u32 v0, v0, s65
	v_readlane_b32 s37, v254, 30
	v_or_b32_e32 v41, v2, v1
	v_lshlrev_b32_e32 v1, 3, v198
	v_ashrrev_i32_e32 v59, 31, v58
	v_add_u32_e32 v38, 0, v0
	v_add_u32_e32 v40, s37, v0
	v_and_b32_e32 v42, 24, v1
	s_lshl_b32 s35, s4, 5
	v_add_u32_e32 v43, s0, v0
	v_add_u32_e32 v44, s1, v0
	v_lshl_add_u64 v[0:1], v[58:59], 1, s[80:81]
	s_mov_b64 s[0:1], 0x5fba4000
	v_lshl_add_u64 v[60:61], v[0:1], 0, s[0:1]
	s_add_u32 s0, s80, 0x48024000
	v_writelane_b32 v255, s0, 22
	v_writelane_b32 v254, s80, 11
	s_addc_u32 s0, s81, 0
	v_mul_lo_u32 v0, v77, s65
	v_writelane_b32 v255, s0, 23
	s_lshl_b32 s0, s82, 3
	v_add_u32_e32 v46, 0, v0
	v_lshlrev_b32_e32 v0, 6, v56
	s_mov_b32 s83, s0
	s_andn2_b32 s0, s0, 31
	v_add3_u32 v0, v2, v0, s0
	s_lshl_b32 s0, s4, 2
	v_cmp_eq_u32_e64 s[38:39], v77, v45
	v_and_or_b32 v2, s0, 4, v0
	s_or_b32 s0, s34, 1
	v_or_b32_e32 v53, 1, v77
	v_writelane_b32 v255, s38, 24
	v_lshl_or_b32 v49, s0, 4, v56
	v_writelane_b32 v254, s81, 12
	v_writelane_b32 v255, s39, 25
	v_cmp_eq_u32_e64 s[38:39], v53, v45
	v_lshlrev_b32_e32 v0, 2, v45
	v_or_b32_e32 v54, 2, v77
	v_lshlrev_b32_e32 v62, 2, v49
	v_writelane_b32 v255, s38, 26
	v_add_u32_e32 v51, s9, v0
	v_add_u32_e32 v68, s9, v62
	v_readlane_b32 s9, v254, 31
	v_writelane_b32 v255, s39, 27
	v_cmp_eq_u32_e64 s[38:39], v54, v45
	v_or_b32_e32 v55, 3, v77
	s_add_i32 s1, s9, s35
	v_writelane_b32 v255, s38, 28
	v_or_b32_e32 v1, 15, v198
	v_mul_lo_u32 v41, v41, s65
	v_add_u32_e32 v70, s1, v42
	v_readlane_b32 s1, v254, 32
	v_writelane_b32 v255, s39, 29
	v_cmp_eq_u32_e64 s[38:39], v55, v45
	s_lshl_b32 s89, s0, 5
	v_mul_lo_u32 v102, v1, s64
	v_add_u32_e32 v1, 0, v41
	v_add_u32_e32 v105, s1, v0
	v_writelane_b32 v255, s38, 30
	v_lshl_add_u32 v0, s34, 10, v2
	v_lshl_add_u32 v2, s0, 10, v2
	s_mul_i32 s0, s82, 0x480
	s_lshl_b32 s91, s34, 5
	v_add_u32_e32 v69, s35, v1
	v_writelane_b32 v255, s39, 31
	v_cmp_eq_u32_e64 s[34:35], v77, v49
	s_add_i32 s0, s0, 0
	v_lshl_add_u32 v108, v198, 1, s0
	v_writelane_b32 v255, s34, 32
	s_lshl_b32 s0, s82, 8
	s_cmp_gt_i32 s82, 0
	v_writelane_b32 v255, s35, 33
	v_writelane_b32 v255, s0, 34
	s_cselect_b64 s[34:35], -1, 0
	v_writelane_b32 v255, s34, 35
	s_cmp_gt_i32 s82, 1
	v_cmp_eq_u32_e32 vcc, 0, v56
	v_writelane_b32 v255, s35, 36
	s_cselect_b64 s[34:35], -1, 0
	v_writelane_b32 v255, s34, 37
	s_cmp_gt_i32 s82, 2
	v_cndmask_b32_e64 v84, 0, 1.0, vcc
	v_writelane_b32 v255, s35, 38
	s_cselect_b64 s[34:35], -1, 0
	v_writelane_b32 v255, s34, 39
	s_cmp_gt_i32 s82, 3
	v_cmp_eq_u32_e32 vcc, 1, v56
	v_writelane_b32 v255, s35, 40
	s_cselect_b64 s[34:35], -1, 0
	v_writelane_b32 v255, s34, 41
	s_cmp_gt_i32 s82, 4
	v_cndmask_b32_e64 v85, 0, 1.0, vcc
	v_writelane_b32 v255, s35, 42
	s_cselect_b64 s[34:35], -1, 0
	v_writelane_b32 v255, s34, 43
	s_cmp_gt_i32 s82, 5
	v_cmp_eq_u32_e32 vcc, 2, v56
	v_writelane_b32 v255, s35, 44
	s_cselect_b64 s[34:35], -1, 0
	v_cndmask_b32_e64 v87, 0, 1.0, vcc
	v_cmp_eq_u32_e32 vcc, 3, v56
	v_writelane_b32 v255, s34, 45
	s_cmp_gt_i32 s82, 6
	v_cndmask_b32_e64 v88, 0, 1.0, vcc
	v_cmp_eq_u32_e32 vcc, 4, v56
	v_writelane_b32 v255, s35, 46
	s_cselect_b64 s[34:35], -1, 0
	v_cndmask_b32_e64 v89, 0, 1.0, vcc
	v_cmp_eq_u32_e32 vcc, 5, v56
	v_writelane_b32 v255, s34, 47
	s_cmp_gt_i32 s82, 7
; __device__ __forceinline__ f32x4 zero4v() { f32x4 z = (f32x4){0.f, 0.f, 0.f, 0.f}; asm volatile("" : "+v"(z)); return z; }
; __device__ __forceinline__ void rwkvA_phase(const Frame& F, int l) {
;     ...
;     int t0 = F.bid, tstride = F.nb, tend = CH_NTASK;
;     if (split) { if (F.bid < RB_BLOCKS) { t0 = RA_NT0 + F.bid; tstride = RB_BLOCKS; } else { t0 = F.bid - RB_BLOCKS; tstride = RA_NONB; tend = RA_NT0; } }
;     if (split && F.bid < RB_BLOCKS) { mla_unit(F, F.bid & 7, (F.bid >> 3) * 256, 0, MLA_SPLIT, 1, F.bid); __syncthreads(); }
;     if (t0 < tend) RA_LOAD(t0);
;     for (int task = t0; task < tend; task += tstride) {
;         const f32x4 z4 = zero4v();
;         const int hd = task / CH_NCH, c = task - hd * CH_NCH, head = hd >> 1, dir = hd & 1;
;         const int ch = head * 64 + F.lane;
;         const float kkc = F.in[I_KK][(size_t)l * AW + ch], kac = F.in[I_KA][(size_t)l * AW + ch];
	v_cndmask_b32_e64 v90, 0, 1.0, vcc
	v_cmp_eq_u32_e32 vcc, 6, v56
	v_writelane_b32 v255, s35, 48
	s_cselect_b64 s[34:35], -1, 0
	v_cndmask_b32_e64 v92, 0, 1.0, vcc
	v_cmp_eq_u32_e32 vcc, 7, v56
	v_writelane_b32 v255, s34, 49
	v_lshlrev_b32_e32 v47, 1, v45
	v_cndmask_b32_e64 v93, 0, 1.0, vcc
	v_cmp_eq_u32_e32 vcc, 8, v56
	v_writelane_b32 v255, s35, 50
	v_cmp_eq_u32_e64 s[34:35], v53, v49
	v_mul_u32_u24_e32 v48, 0x90, v45
	v_cmp_lt_i32_e64 s[4:5], v45, v77
	v_cmp_gt_i32_e64 s[6:7], v45, v77
	v_cmp_gt_i32_e64 s[10:11], v45, v53
	v_cmp_lt_i32_e64 s[86:87], v45, v54
	v_cmp_gt_i32_e64 s[12:13], v45, v54
	v_cmp_lt_i32_e64 s[14:15], v45, v55
	v_cmp_gt_i32_e64 s[16:17], v45, v55
	v_cndmask_b32_e64 v94, 0, 1.0, vcc
	v_cmp_eq_u32_e32 vcc, 9, v56
	v_writelane_b32 v255, s34, 51
	v_lshlrev_b32_e32 v45, 2, v198
	v_readlane_b32 s0, v254, 33
	v_cndmask_b32_e64 v95, 0, 1.0, vcc
	v_cmp_eq_u32_e32 vcc, 10, v56
	v_add_u32_e32 v107, s1, v62
	v_writelane_b32 v255, s35, 52
	v_add_u32_e32 v109, s0, v45
	v_add_u32_e32 v110, s1, v45
	v_cmp_eq_u32_e64 s[0:1], v54, v49
	v_cndmask_b32_e64 v96, 0, 1.0, vcc
	v_cmp_eq_u32_e32 vcc, 11, v56
	v_writelane_b32 v255, s0, 53
	v_add_u32_e32 v104, v1, v42
	v_cndmask_b32_e64 v97, 0, 1.0, vcc
	v_cmp_eq_u32_e32 vcc, 12, v56
	v_writelane_b32 v255, s1, 54
	v_cmp_eq_u32_e64 s[0:1], v55, v49
	v_cndmask_b32_e64 v98, 0, 1.0, vcc
	v_cmp_eq_u32_e32 vcc, 13, v56
	v_writelane_b32 v255, s0, 55
	v_add_u32_e32 v1, s9, v42
	v_cndmask_b32_e64 v99, 0, 1.0, vcc
	v_cmp_eq_u32_e32 vcc, 14, v56
	v_and_b32_e32 v45, 63, v198
	v_writelane_b32 v255, s1, 56
	v_cmp_gt_i32_e64 s[0:1], s33, v200
	v_add_u32_e32 v39, 0, v75
	v_mul_u32_u24_e32 v50, 0x90, v49
	v_mul_lo_u32 v52, v77, s64
	v_cndmask_b32_e64 v100, 0, 1.0, vcc
	v_cmp_eq_u32_e32 vcc, 15, v56
	v_add_u32_e32 v71, s91, v1
	v_add_u32_e32 v72, s89, v1
	v_ashrrev_i32_e32 v1, 31, v0
	s_cmp_eq_u32 s82, 0
	v_add_u32_e32 v62, s3, v3
	v_ashrrev_i32_e32 v3, 31, v2
	v_lshl_add_u32 v64, v45, 2, s8
	v_lshl_add_u32 v66, v45, 1, s37
	v_mul_u32_u24_e32 v45, 0x110, v56
	v_mul_lo_u32 v36, v36, s64
	v_writelane_b32 v255, s0, 57
	v_cmp_lt_i32_e64 s[18:19], v49, v77
	v_cmp_gt_i32_e64 s[20:21], v49, v77
	v_cmp_gt_i32_e64 s[22:23], v49, v53
	v_cmp_lt_i32_e64 s[24:25], v49, v54
	v_cmp_gt_i32_e64 s[26:27], v49, v54
	v_cmp_lt_i32_e64 s[28:29], v49, v55
	v_cmp_gt_i32_e64 s[30:31], v49, v55
	v_mul_lo_u32 v86, v75, s64
	v_cndmask_b32_e64 v101, 0, 1.0, vcc
	v_add3_u32 v103, 0, v42, v41
	s_cselect_b64 s[92:93], -1, 0
	s_lshl_b32 s72, s36, 2
	v_bfe_u32 v111, v198, 4, 2
	v_add3_u32 v112, v45, v76, 0
	v_add3_u32 v113, v36, v37, 0
	v_add_u32_e32 v114, v39, v48
	v_add_u32_e32 v115, v39, v50
	v_add_u32_e32 v116, v51, v52
	v_add_u32_e32 v117, v68, v52
	v_add_u32_e32 v118, v40, v75
	v_add_u32_e32 v119, v69, v42
	v_add_u32_e32 v120, v43, v75
	v_add_u32_e32 v121, v44, v75
	v_add_u32_e32 v122, v70, v41
	v_add_u32_e32 v123, v71, v41
	v_add_u32_e32 v124, v72, v41
	v_lshlrev_b32_e32 v68, 2, v56
	v_lshlrev_b64 v[70:71], 1, v[0:1]
	v_lshlrev_b64 v[72:73], 1, v[2:3]
	v_add_u32_e32 v125, v38, v75
	v_add_u32_e32 v126, v46, v47
	s_waitcnt vmcnt(0) lgkmcnt(0)
	v_mov_b32_e32 v127, v4
	v_mov_b32_e32 v140, v5
	v_mov_b32_e32 v143, v6
	v_mov_b32_e32 v147, v7
	v_mov_b32_e32 v153, v8
	v_mov_b32_e32 v155, v9
	v_mov_b32_e32 v160, v10
	v_mov_b32_e32 v166, v11
	v_mov_b32_e32 v136, v35
	v_mov_b32_e32 v141, v34
	v_mov_b32_e32 v144, v32
	v_mov_b32_e32 v148, v29
	v_mov_b32_e32 v154, v28
	v_mov_b32_e32 v156, v25
	v_mov_b32_e32 v161, v24
	v_mov_b32_e32 v163, v21
	v_mov_b32_e32 v137, v12
	v_mov_b32_e32 v142, v14
	v_mov_b32_e32 v146, v13
	v_mov_b32_e32 v149, v16
	v_mov_b32_e32 v152, v15
	v_mov_b32_e32 v158, v17
	v_mov_b32_e32 v162, v19
	v_mov_b32_e32 v165, v18
	v_mov_b32_e32 v138, v33
	v_mov_b32_e32 v139, v31
	v_mov_b32_e32 v145, v30
	v_mov_b32_e32 v150, v27
	v_mov_b32_e32 v151, v26
	v_mov_b32_e32 v157, v23
	v_mov_b32_e32 v159, v22
	v_mov_b32_e32 v164, v20
	s_mul_i32 s43, s82, 0x1140
	v_writelane_b32 v255, s1, 58
	s_mul_hi_i32 s36, s2, 0x3e0f83e1
	s_lshr_b32 s37, s36, 31
	s_ashr_i32 s36, s36, 5
	s_add_i32 s37, s36, s37
	s_lshl_b32 s36, s37, 5
	s_andn2_b32 s36, s36, 63
	v_add_u32_e32 v202, s36, v198
	v_readlane_b32 s38, v255, 14
	v_ashrrev_i32_e32 v203, 31, v202
	v_readlane_b32 s39, v255, 15
	v_readlane_b32 s40, v253, 56
	v_readlane_b32 s41, v253, 57
	s_nop 1
	v_lshl_add_u64 v[202:203], v[202:203], 0, s[38:39]
	v_lshlrev_b64 v[202:203], 2, v[202:203]
	v_lshl_add_u64 v[204:205], s[40:41], 0, v[202:203]
	global_load_dword v250, v[204:205], off
	v_readlane_b32 s40, v253, 58
	v_readlane_b32 s41, v253, 59
	s_nop 1
	v_lshl_add_u64 v[202:203], s[40:41], 0, v[202:203]
	global_load_dword v251, v[202:203], off
	s_waitcnt vmcnt(0)
	s_branch .LBB0_750

; __device__ __forceinline__ float sigmoidf_(float x) { return __builtin_amdgcn_rcpf(1.0f + __expf(-x)); }
; __device__ __forceinline__ void rwkvA_phase(const Frame& F, int l) {
;     ...
;         const int ch = head * 64 + F.lane;
;         const float kkc = F.in[I_KK][(size_t)l * AW + ch], kac = F.in[I_KA][(size_t)l * AW + ch];
;         {
;             float kk_[8], b_[8], kd_[8], r_[8], lw_[8], cl_[8];
;             float run = 0.f;
; #pragma unroll
;             for (int e = 0; e < 8; ++e) {
;                 const int i = F.wave * 8 + e;
;                 const float k = pk_[e], a = sigmoidf_(pza_[e]);
;                 lw_[e] = -0.6065306597126334f * sigmoidf_(pzw_[e]);
;                 r_[e] = pr_[e];
;                 const float kkr = k * kkc;
;                 const float nrm = sqrtf(wave_sum(kkr * kkr, F.lane));
;                 kk_[e] = kkr * __builtin_amdgcn_rcpf(fmaxf(nrm, 1e-12f));
.LBB0_750:
	s_mul_hi_i32 s0, s2, 0x3e0f83e1
	s_lshr_b32 s1, s0, 31
	s_ashr_i32 s0, s0, 5
	s_add_i32 s1, s0, s1
	s_lshl_b32 s0, s1, 5
	s_andn2_b32 s0, s0, 63
	v_add_u32_e32 v36, s0, v198
	v_readlane_b32 s34, v255, 14
	v_ashrrev_i32_e32 v37, 31, v36
	v_readlane_b32 s35, v255, 15
	s_mov_b64 s[94:95], s[74:75]
	s_mov_b64 s[8:9], s[72:73]
	v_mov_b32_e32 v129, v128
	v_lshl_add_u64 v[36:37], v[36:37], 0, s[34:35]
	v_readlane_b32 s60, v253, 42
	v_mov_b32_e32 v130, v128
	v_mov_b32_e32 v131, v128
	v_mov_b64_e32 v[0:1], v[128:129]
	v_lshlrev_b64 v[36:37], 2, v[36:37]
	v_readlane_b32 s74, v253, 56
	v_readlane_b32 s75, v253, 57
	v_mov_b64_e32 v[2:3], v[130:131]
	v_readlane_b32 s61, v253, 43
	v_lshl_add_u64 v[38:39], s[74:75], 0, v[36:37]
	s_nop 0
	v_readlane_b32 s62, v253, 44
	v_readlane_b32 s63, v253, 45
	v_readlane_b32 s64, v253, 46
	v_readlane_b32 s65, v253, 47
	v_readlane_b32 s66, v253, 48
	v_readlane_b32 s67, v253, 49
	v_readlane_b32 s68, v253, 50
	v_readlane_b32 s69, v253, 51
	v_readlane_b32 s70, v253, 52
	v_readlane_b32 s71, v253, 53
	v_readlane_b32 s72, v253, 54
	v_readlane_b32 s73, v253, 55
	v_readlane_b32 s60, v253, 58
	v_readlane_b32 s61, v253, 59
	v_readlane_b32 s62, v253, 60
	v_readlane_b32 s70, v254, 4
	v_lshl_add_u64 v[36:37], s[60:61], 0, v[36:37]
	s_nop 0
	v_readlane_b32 s71, v254, 5
	v_readlane_b32 s67, v254, 1
	v_readlane_b32 s34, v255, 4
	s_add_i32 s42, s2, s34
	s_cmp_ge_i32 s42, s85
	v_readlane_b32 s63, v253, 61
	v_readlane_b32 s64, v253, 62
	v_readlane_b32 s65, v253, 63
	v_readlane_b32 s66, v254, 0
	s_cselect_b64 s[34:35], -1, 0
	s_and_b64 vcc, exec, s[34:35]
	v_readlane_b32 s68, v254, 2
	v_readlane_b32 s69, v254, 3
	v_readlane_b32 s72, v254, 6
	v_readlane_b32 s73, v254, 7
	v_readlane_b32 s74, v254, 8
	v_readlane_b32 s75, v254, 9
	s_waitcnt vmcnt(28)
	v_mov_b32_e32 v44, v250
	v_mov_b32_e32 v36, v251
	v_mul_f32_e32 v43, v33, v44
	v_mul_f32_e32 v37, v43, v43
	v_mul_f32_e32 v42, v31, v44
	v_mul_f32_e32 v41, v30, v44
	v_mov_b32_dpp v37, v37 quad_perm:[1,0,3,2] row_mask:0xf bank_mask:0xf bound_ctrl:1
	v_fmac_f32_e32 v37, v43, v43
	v_mul_f32_e32 v40, v27, v44
	v_mul_f32_e32 v38, v26, v44
	v_add_f32_dpp v37, v37, v37 quad_perm:[2,3,0,1] row_mask:0xf bank_mask:0xf bound_ctrl:1
	s_nop 1
	v_add_f32_dpp v37, v37, v37 row_half_mirror row_mask:0xf bank_mask:0xf bound_ctrl:1
	s_nop 1
	v_add_f32_dpp v37, v37, v37 row_mirror row_mask:0xf bank_mask:0xf bound_ctrl:1
	s_nop 0
	v_readlane_b32 s61, v37, 0
	v_readlane_b32 s71, v37, 16
	v_readlane_b32 s70, v37, 32
	v_readlane_b32 s62, v37, 48
	v_cvt_pk_bf16_f32 v37, v57, s0
	ds_write_b16 v108, v37 offset:36864
	v_mul_f32_e32 v37, v42, v42
	s_nop 1
	v_mov_b32_dpp v37, v37 quad_perm:[1,0,3,2] row_mask:0xf bank_mask:0xf bound_ctrl:1
	v_fmac_f32_e32 v37, v42, v42
	s_nop 1
	v_add_f32_dpp v37, v37, v37 quad_perm:[2,3,0,1] row_mask:0xf bank_mask:0xf bound_ctrl:1
	s_nop 1
	v_add_f32_dpp v37, v37, v37 row_half_mirror row_mask:0xf bank_mask:0xf bound_ctrl:1
	s_nop 1
	v_add_f32_dpp v37, v37, v37 row_mirror row_mask:0xf bank_mask:0xf bound_ctrl:1
	s_nop 0
	v_readlane_b32 s39, v37, 0
	v_readlane_b32 s41, v37, 16
	v_readlane_b32 s40, v37, 32
	v_readlane_b32 s60, v37, 48
	v_cvt_pk_bf16_f32 v37, v63, s0
	ds_write_b16 v108, v37 offset:37008
	v_mul_f32_e32 v37, v41, v41
	s_nop 1
	v_mov_b32_dpp v37, v37 quad_perm:[1,0,3,2] row_mask:0xf bank_mask:0xf bound_ctrl:1
	v_fmac_f32_e32 v37, v41, v41
	s_nop 1
	v_add_f32_dpp v37, v37, v37 quad_perm:[2,3,0,1] row_mask:0xf bank_mask:0xf bound_ctrl:1
	s_nop 1
	v_add_f32_dpp v37, v37, v37 row_half_mirror row_mask:0xf bank_mask:0xf bound_ctrl:1
	s_nop 1
	v_add_f32_dpp v37, v37, v37 row_mirror row_mask:0xf bank_mask:0xf bound_ctrl:1
	s_nop 0
	v_readlane_b32 s53, v37, 0
	v_readlane_b32 s55, v37, 16
	v_readlane_b32 s54, v37, 32
	v_readlane_b32 s38, v37, 48
	v_cvt_pk_bf16_f32 v37, v65, s0
	ds_write_b16 v108, v37 offset:37152
	v_mul_f32_e32 v37, v40, v40
	s_nop 1
	v_mov_b32_dpp v37, v37 quad_perm:[1,0,3,2] row_mask:0xf bank_mask:0xf bound_ctrl:1
	v_fmac_f32_e32 v37, v40, v40
	s_nop 1
	v_add_f32_dpp v37, v37, v37 quad_perm:[2,3,0,1] row_mask:0xf bank_mask:0xf bound_ctrl:1
	s_nop 1
	v_add_f32_dpp v37, v37, v37 row_half_mirror row_mask:0xf bank_mask:0xf bound_ctrl:1
	s_nop 1
	v_add_f32_dpp v37, v37, v37 row_mirror row_mask:0xf bank_mask:0xf bound_ctrl:1
	s_nop 0
	v_readlane_b32 s49, v37, 0
	v_readlane_b32 s51, v37, 16
	v_readlane_b32 s50, v37, 32
	v_readlane_b32 s52, v37, 48
	v_cvt_pk_bf16_f32 v37, v67, s0
	ds_write_b16 v108, v37 offset:37296
	v_mul_f32_e32 v37, v38, v38
	s_nop 1
	v_mov_b32_dpp v37, v37 quad_perm:[1,0,3,2] row_mask:0xf bank_mask:0xf bound_ctrl:1
	v_fmac_f32_e32 v37, v38, v38
	s_nop 1
	v_add_f32_dpp v37, v37, v37 quad_perm:[2,3,0,1] row_mask:0xf bank_mask:0xf bound_ctrl:1
	s_nop 1
	v_add_f32_dpp v37, v37, v37 row_half_mirror row_mask:0xf bank_mask:0xf bound_ctrl:1
	s_nop 1
	v_add_f32_dpp v37, v37, v37 row_mirror row_mask:0xf bank_mask:0xf bound_ctrl:1
	s_nop 0
	v_readlane_b32 s45, v37, 0
	v_readlane_b32 s47, v37, 16
	v_readlane_b32 s46, v37, 32
	v_readlane_b32 s48, v37, 48
	v_cvt_pk_bf16_f32 v37, v74, s0
	ds_write_b16 v108, v37 offset:37440
	v_mul_f32_e32 v37, v23, v44
	v_mul_f32_e32 v39, v37, v37
	s_nop 1
	v_mov_b32_dpp v39, v39 quad_perm:[1,0,3,2] row_mask:0xf bank_mask:0xf bound_ctrl:1
	v_fmac_f32_e32 v39, v37, v37
	s_nop 1
	v_add_f32_dpp v39, v39, v39 quad_perm:[2,3,0,1] row_mask:0xf bank_mask:0xf bound_ctrl:1
	s_nop 1
	v_add_f32_dpp v39, v39, v39 row_half_mirror row_mask:0xf bank_mask:0xf bound_ctrl:1
	s_nop 1
	v_add_f32_dpp v39, v39, v39 row_mirror row_mask:0xf bank_mask:0xf bound_ctrl:1
	s_nop 0
	v_readlane_b32 s3, v39, 0
	v_readlane_b32 s37, v39, 16
	v_readlane_b32 s36, v39, 32
; #define LAS __attribute__((address_space(3)))
; __device__ __forceinline__ void rwkvA_phase(const Frame& F, int l) {
;     ...
;                 const float kkr = k * kkc;
;                 const float nrm = sqrtf(wave_sum(kkr * kkr, F.lane));
;                 kk_[e] = kkr * __builtin_amdgcn_rcpf(fmaxf(nrm, 1e-12f));
;                 b_[e] = kk_[e] * a;
;                 kd_[e] = k * (1.0f + (a - 1.0f) * kac);
;                 run += lw_[e]; cl_[e] = run;
;                 *(LAS bf16_t*)(L + O_V + i * CS + F.lane * 2) = f2bf(pv_[e]);
;             }
;             if (task + tstride < tend) RA_LOAD(task + tstride);
	v_readlane_b32 s44, v39, 48
	v_cvt_pk_bf16_f32 v39, v78, s0
	ds_write_b16 v108, v39 offset:37584
	v_mul_f32_e32 v39, v22, v44
	v_mul_f32_e32 v45, v39, v39
	v_mul_f32_e32 v44, v20, v44
	s_nop 0
	v_mov_b32_dpp v45, v45 quad_perm:[1,0,3,2] row_mask:0xf bank_mask:0xf bound_ctrl:1
	v_fmac_f32_e32 v45, v39, v39
	s_nop 1
	v_add_f32_dpp v45, v45, v45 quad_perm:[2,3,0,1] row_mask:0xf bank_mask:0xf bound_ctrl:1
	s_nop 1
	v_add_f32_dpp v45, v45, v45 row_half_mirror row_mask:0xf bank_mask:0xf bound_ctrl:1
	s_nop 1
	v_add_f32_dpp v45, v45, v45 row_mirror row_mask:0xf bank_mask:0xf bound_ctrl:1
	s_nop 0
	v_readlane_b32 s67, v45, 0
	v_readlane_b32 s81, v45, 16
	v_readlane_b32 s80, v45, 32
	v_readlane_b32 s58, v45, 48
	v_cvt_pk_bf16_f32 v45, v91, s0
	ds_write_b16 v108, v45 offset:37728
	v_mul_f32_e32 v45, v44, v44
	s_nop 1
	v_mov_b32_dpp v45, v45 quad_perm:[1,0,3,2] row_mask:0xf bank_mask:0xf bound_ctrl:1
	v_fmac_f32_e32 v45, v44, v44
	s_nop 1
	v_add_f32_dpp v45, v45, v45 quad_perm:[2,3,0,1] row_mask:0xf bank_mask:0xf bound_ctrl:1
	s_nop 1
	v_add_f32_dpp v45, v45, v45 row_half_mirror row_mask:0xf bank_mask:0xf bound_ctrl:1
	s_nop 1
	v_add_f32_dpp v45, v45, v45 row_mirror row_mask:0xf bank_mask:0xf bound_ctrl:1
	s_nop 0
	v_readlane_b32 s63, v45, 0
	v_readlane_b32 s65, v45, 16
	v_readlane_b32 s64, v45, 32
	v_readlane_b32 s66, v45, 48
	v_cvt_pk_bf16_f32 v45, v106, s0
	ds_write_b16 v108, v45 offset:37872
	s_cbranch_vccnz .LBB0_752
	s_mul_hi_i32 s68, s42, 0x3e0f83e1
	s_lshr_b32 s69, s68, 31
	s_ashr_i32 s68, s68, 5
	s_add_i32 s56, s68, s69
	s_mul_i32 s68, s56, 0xffffff7c
	s_add_i32 s68, s68, s42
	s_lshl_b32 s68, s68, 6
	s_bfe_i32 s69, s56, 0x10000
	s_mov_b32 s76, s96
	s_and_b32 s96, s56, 1
	s_add_i32 s68, s68, s83
	s_cmpk_lt_i32 s68, 0x100
	s_movk_i32 s72, 0xff00
	s_mov_b32 s77, s97
	s_cselect_b32 s97, 0x2000, s72
	s_add_i32 s97, s97, s68
	s_sub_i32 s68, 0x20ff, s68
	s_cmp_eq_u32 s96, 0
	s_cselect_b32 vcc_lo, s97, s68
	s_movk_i32 s68, 0xf000
	s_cselect_b32 s68, 0x1000, s68
	s_lshl_b32 s56, s56, 5
	s_ashr_i32 vcc_hi, vcc_lo, 31
	s_andn2_b32 s56, s56, 63
	s_lshl_b64 vcc, vcc, 10
	s_ashr_i32 s97, s56, 31
	s_add_u32 vcc_lo, vcc_lo, s56
	s_addc_u32 vcc_hi, vcc_hi, s97
	v_lshl_add_u64 v[46:47], vcc, 0, v[198:199]
	v_readlane_b32 s72, v255, 8
	v_lshlrev_b64 v[46:47], 2, v[46:47]
	v_readlane_b32 s73, v255, 9
	s_mul_i32 s96, s96, 0x2100000
	v_readlane_b32 s56, v255, 18
	v_lshl_add_u64 v[48:49], s[72:73], 0, v[46:47]
	v_readlane_b32 s72, v255, 10
	s_add_u32 vcc_lo, s56, s96
	v_readlane_b32 s56, v255, 19
	v_readlane_b32 s73, v255, 11
	s_addc_u32 vcc_hi, s56, 0
	v_readlane_b32 s56, v255, 20
	v_lshl_add_u64 v[50:51], s[72:73], 0, v[46:47]
	v_readlane_b32 s72, v255, 6
	v_lshl_add_u64 v[54:55], vcc, 0, v[46:47]
	s_add_u32 vcc_lo, s56, s96
	v_readlane_b32 s56, v255, 21
	v_readlane_b32 s73, v255, 7
	s_addc_u32 vcc_hi, s56, 0
	s_mov_b32 s97, s77
	v_lshl_add_u64 v[52:53], s[72:73], 0, v[46:47]
	v_lshl_add_u64 v[46:47], vcc, 0, v[46:47]
	flat_load_dword v138, v[48:49]
	flat_load_dword v57, v[50:51]
	flat_load_dword v137, v[52:53]
	flat_load_dword v136, v[46:47]
	flat_load_dword v127, v[54:55]
	v_lshl_add_u64 v[48:49], v[48:49], 0, s[68:69]
	v_lshl_add_u64 v[50:51], v[50:51], 0, s[68:69]
	v_lshl_add_u64 v[46:47], v[46:47], 0, s[68:69]
	v_lshl_add_u64 v[54:55], v[54:55], 0, s[68:69]
	flat_load_dword v139, v[48:49]
	flat_load_dword v63, v[50:51]
	flat_load_dword v140, v[54:55]
	flat_load_dword v141, v[46:47]
	v_lshl_add_u64 v[48:49], v[48:49], 0, s[68:69]
	v_lshl_add_u64 v[50:51], v[50:51], 0, s[68:69]
	v_lshl_add_u64 v[46:47], v[46:47], 0, s[68:69]
	v_lshl_add_u64 v[54:55], v[54:55], 0, s[68:69]
	flat_load_dword v145, v[48:49]
	flat_load_dword v65, v[50:51]
	flat_load_dword v143, v[54:55]
	flat_load_dword v144, v[46:47]
	v_lshl_add_u64 v[48:49], v[48:49], 0, s[68:69]
	v_lshl_add_u64 v[50:51], v[50:51], 0, s[68:69]
	v_lshl_add_u64 v[46:47], v[46:47], 0, s[68:69]
	v_lshl_add_u64 v[54:55], v[54:55], 0, s[68:69]
	flat_load_dword v150, v[48:49]
	flat_load_dword v67, v[50:51]
	flat_load_dword v147, v[54:55]
	flat_load_dword v148, v[46:47]
	v_lshl_add_u64 v[48:49], v[48:49], 0, s[68:69]
	v_lshl_add_u64 v[50:51], v[50:51], 0, s[68:69]
	v_lshl_add_u64 v[46:47], v[46:47], 0, s[68:69]
	v_lshl_add_u64 v[54:55], v[54:55], 0, s[68:69]
	flat_load_dword v151, v[48:49]
	flat_load_dword v74, v[50:51]
	flat_load_dword v153, v[54:55]
	flat_load_dword v154, v[46:47]
	v_lshl_add_u64 v[48:49], v[48:49], 0, s[68:69]
	v_lshl_add_u64 v[50:51], v[50:51], 0, s[68:69]
	v_lshl_add_u64 v[46:47], v[46:47], 0, s[68:69]
	v_lshl_add_u64 v[54:55], v[54:55], 0, s[68:69]
	flat_load_dword v157, v[48:49]
	flat_load_dword v78, v[50:51]
	flat_load_dword v155, v[54:55]
	flat_load_dword v156, v[46:47]
	v_lshl_add_u64 v[48:49], v[48:49], 0, s[68:69]
	v_lshl_add_u64 v[50:51], v[50:51], 0, s[68:69]
	v_lshl_add_u64 v[46:47], v[46:47], 0, s[68:69]
	v_lshl_add_u64 v[54:55], v[54:55], 0, s[68:69]
	v_lshl_add_u64 v[52:53], v[52:53], 0, s[68:69]
	flat_load_dword v159, v[48:49]
	flat_load_dword v91, v[50:51]
	flat_load_dword v160, v[54:55]
	flat_load_dword v161, v[46:47]
	v_lshl_add_u64 v[48:49], v[48:49], 0, s[68:69]
	v_lshl_add_u64 v[46:47], v[46:47], 0, s[68:69]
	flat_load_dword v142, v[52:53]
	flat_load_dword v164, v[48:49]
	flat_load_dword v163, v[46:47]
	v_lshl_add_u64 v[52:53], v[52:53], 0, s[68:69]
	v_lshl_add_u64 v[48:49], v[50:51], 0, s[68:69]
	flat_load_dword v146, v[52:53]
	flat_load_dword v106, v[48:49]
	v_lshl_add_u64 v[52:53], v[52:53], 0, s[68:69]
	flat_load_dword v149, v[52:53]
	v_lshl_add_u64 v[52:53], v[52:53], 0, s[68:69]
	flat_load_dword v152, v[52:53]
	v_lshl_add_u64 v[52:53], v[52:53], 0, s[68:69]
	flat_load_dword v158, v[52:53]
	v_lshl_add_u64 v[52:53], v[52:53], 0, s[68:69]
	v_lshl_add_u64 v[46:47], v[54:55], 0, s[68:69]
	flat_load_dword v166, v[46:47]
	v_lshl_add_u64 v[48:49], v[52:53], 0, s[68:69]
	flat_load_dword v162, v[52:53]
	flat_load_dword v165, v[48:49]
	s_mov_b32 s96, s76
	v_readlane_b32 s76, v254, 57
	v_readlane_b32 s77, v254, 58

; __device__ __forceinline__ void lds_barrier() { asm volatile("s_waitcnt lgkmcnt(0)\n\ts_barrier" ::: "memory"); }
; #define MFMA_BF(a, b, c) __builtin_amdgcn_mfma_f32_16x16x32_bf16(a, b, c, 0, 0, 0)
; __device__ __forceinline__ void rwkvA_phase(const Frame& F, int l) {
;     ...
;         {
;             f32x4 av[2] = {z4, z4}, p[2] = {z4, z4};
; #pragma unroll
;             for (int ks = 0; ks < 2; ++ks) {
;                 const bf16x8 aA = ch_rowread(L + O_AAK, tr, ks, qi, g), aT = ch_rowread(L + O_T, tr, ks, qi, g);
; #pragma unroll
;                 for (int t = 0; t < 2; ++t) { av[t] = MFMA_BF(aA, ch_trread(L + O_V, tcb + t, ks, qi, g), av[t]); p[t] = MFMA_BF(aT, ch_trread(L + O_KT, tcb + t, ks, qi, g), p[t]); }
;             }
; #pragma unroll
;             for (int t = 0; t < 2; ++t) { ch_store_bf16(L + O_BB, tr, tcb + t, qi, g, av[t]); ch_store_bf16(L + O_KB, tr, tcb + t, qi, g, p[t]); }
;         }
;         lds_barrier();
;         {
;             f32x4 q[2] = {z4, z4};
; #pragma unroll
;             for (int ks = 0; ks < 2; ++ks) {
;                 const bf16x8 aT = ch_rowread(L + O_T, tr, ks, qi, g);
; #pragma unroll
;                 for (int t = 0; t < 2; ++t) q[t] = MFMA_BF(aT, ch_trread(L + O_BB, tcb + t, ks, qi, g), q[t]);
;             }
; #pragma unroll
;             for (int t = 0; t < 2; ++t) ch_store_bf16(L + O_AAK, tr, tcb + t, qi, g, q[t]);
;         }
;         lds_barrier();
.LBB0_767:
	s_or_b64 exec, exec, s[68:69]
	s_waitcnt lgkmcnt(0)
	s_barrier
	ds_read_b128 v[4:7], v125 offset:64512
	v_add_u32_e32 v16, s91, v103
	v_add_u32_e32 v69, s89, v103
	ds_read_b64_tr_b16 v[10:11], v16 offset:36864
	ds_read_b64_tr_b16 v[12:13], v16 offset:37440
	ds_read_b128 v[18:21], v118
	ds_read_b64_tr_b16 v[22:23], v16
	ds_read_b64_tr_b16 v[24:25], v16 offset:576
	ds_read_b64_tr_b16 v[26:27], v69 offset:36864
	ds_read_b64_tr_b16 v[28:29], v69 offset:37440
	s_waitcnt lgkmcnt(2)
	v_mfma_f32_16x16x32_bf16 v[22:25], v[18:21], v[22:25], v[0:3]
	v_add_u32_e32 v129, s91, v104
	v_add_u32_e32 v130, s89, v104
	v_readlane_b32 s8, v255, 24
	v_mfma_f32_16x16x32_bf16 v[10:13], v[4:7], v[10:13], v[0:3]
	v_readlane_b32 s9, v255, 25
	s_waitcnt lgkmcnt(0)
	v_mfma_f32_16x16x32_bf16 v[4:7], v[4:7], v[26:29], v[0:3]
	ds_read_b64_tr_b16 v[26:27], v69
	ds_read_b64_tr_b16 v[28:29], v69 offset:576
	ds_read_b128 v[30:33], v125 offset:64576
	s_waitcnt lgkmcnt(1)
	v_mfma_f32_16x16x32_bf16 v[18:21], v[18:21], v[26:29], v[0:3]
	ds_read_b64_tr_b16 v[26:27], v16 offset:41472
	ds_read_b64_tr_b16 v[28:29], v16 offset:42048
	ds_read_b128 v[34:37], v118 offset:64
	s_waitcnt lgkmcnt(1)
	v_mfma_f32_16x16x32_bf16 v[10:13], v[30:33], v[26:29], v[10:13]
	ds_read_b64_tr_b16 v[26:27], v16 offset:4608
	ds_read_b64_tr_b16 v[28:29], v16 offset:5184
	s_waitcnt lgkmcnt(0)
	v_mfma_f32_16x16x32_bf16 v[22:25], v[34:37], v[26:29], v[22:25]
	ds_read_b64_tr_b16 v[26:27], v69 offset:41472
	ds_read_b64_tr_b16 v[28:29], v69 offset:42048
	s_nop 1
	v_cvt_pk_bf16_f32 v10, v10, s0
	s_waitcnt lgkmcnt(0)
	v_mfma_f32_16x16x32_bf16 v[4:7], v[30:33], v[26:29], v[4:7]
	ds_read_b64_tr_b16 v[26:27], v69 offset:4608
	ds_read_b64_tr_b16 v[28:29], v69 offset:5184
	ds_write_b16 v8, v10 offset:46080
	v_cvt_pk_bf16_f32 v10, v11, s0
	s_waitcnt lgkmcnt(1)
	v_mfma_f32_16x16x32_bf16 v[18:21], v[34:37], v[26:29], v[18:21]
	s_nop 1
	v_cvt_pk_bf16_f32 v4, v4, s0
	ds_write_b16 v9, v4 offset:46080
	v_cvt_pk_bf16_f32 v4, v5, s0
	ds_write_b16 v8, v10 offset:46224
	v_cvt_pk_bf16_f32 v10, v12, s0
	ds_write_b16 v9, v4 offset:46224
	v_cvt_pk_bf16_f32 v4, v6, s0
	ds_write_b16 v8, v10 offset:46368
	v_cvt_pk_bf16_f32 v10, v13, s0
	ds_write_b16 v9, v4 offset:46368
	v_cvt_pk_bf16_f32 v4, v7, s0
	ds_write_b16 v8, v10 offset:46512
	v_cvt_pk_bf16_f32 v10, v22, s0
	ds_write_b16 v9, v4 offset:46512
	v_cvt_pk_bf16_f32 v4, v18, s0
	ds_write_b16 v8, v10 offset:55296
	v_cvt_pk_bf16_f32 v10, v23, s0
	ds_write_b16 v9, v4 offset:55296
	v_cvt_pk_bf16_f32 v4, v19, s0
	ds_write_b16 v8, v10 offset:55440
	v_cvt_pk_bf16_f32 v10, v24, s0
	ds_write_b16 v9, v4 offset:55440
	v_cvt_pk_bf16_f32 v4, v20, s0
	ds_write_b16 v8, v10 offset:55584
	v_cvt_pk_bf16_f32 v10, v25, s0
	ds_write_b16 v9, v4 offset:55584
	v_cvt_pk_bf16_f32 v4, v21, s0
	ds_write_b16 v8, v10 offset:55728
	ds_write_b16 v9, v4 offset:55728
	s_waitcnt lgkmcnt(0)
	s_barrier
	ds_read_b128 v[4:7], v118
	ds_read_b64_tr_b16 v[10:11], v16 offset:46080
	ds_read_b64_tr_b16 v[12:13], v16 offset:46656
	ds_read_b64_tr_b16 v[18:19], v69 offset:46080
	ds_read_b64_tr_b16 v[20:21], v69 offset:46656
	ds_read_b128 v[22:25], v118 offset:64
	s_waitcnt lgkmcnt(3)
	v_mfma_f32_16x16x32_bf16 v[10:13], v[4:7], v[10:13], v[0:3]
	s_waitcnt lgkmcnt(1)
	v_mfma_f32_16x16x32_bf16 v[4:7], v[4:7], v[18:21], v[0:3]
	ds_read_b64_tr_b16 v[18:19], v16 offset:50688
	ds_read_b64_tr_b16 v[20:21], v16 offset:51264
	s_waitcnt lgkmcnt(0)
	v_mfma_f32_16x16x32_bf16 v[10:13], v[22:25], v[18:21], v[10:13]
	ds_read_b64_tr_b16 v[18:19], v69 offset:50688
	ds_read_b64_tr_b16 v[20:21], v69 offset:51264
	s_waitcnt lgkmcnt(0)
	v_mfma_f32_16x16x32_bf16 v[4:7], v[22:25], v[18:21], v[4:7]
	s_nop 3
	v_cvt_pk_bf16_f32 v10, v10, s0
	ds_write_b16 v8, v10 offset:64512
	v_cvt_pk_bf16_f32 v10, v11, s0
	s_nop 0
	v_cvt_pk_bf16_f32 v4, v4, s0
	ds_write_b16 v9, v4 offset:64512
	v_cvt_pk_bf16_f32 v4, v5, s0
	ds_write_b16 v8, v10 offset:64656
	v_cvt_pk_bf16_f32 v10, v12, s0
	ds_write_b16 v9, v4 offset:64656
	v_cvt_pk_bf16_f32 v4, v6, s0
	ds_write_b16 v8, v10 offset:64800
	v_cvt_pk_bf16_f32 v10, v13, s0
	ds_write_b16 v9, v4 offset:64800
	v_cvt_pk_bf16_f32 v4, v7, s0
	ds_write_b16 v8, v10 offset:64944
	ds_write_b16 v9, v4 offset:64944
	s_waitcnt lgkmcnt(0)
	s_barrier
	s_cmp_ge_i32 s42, s85
	s_cbranch_scc1 .Lmy_pf_skip
	s_mul_hi_i32 s36, s42, 0x3e0f83e1
	s_lshr_b32 s37, s36, 31
	s_ashr_i32 s36, s36, 5
	s_add_i32 s37, s36, s37
	s_lshl_b32 s36, s37, 5
	s_andn2_b32 s36, s36, 63
	v_add_u32_e32 v202, s36, v198
	v_readlane_b32 s38, v255, 14
	v_ashrrev_i32_e32 v203, 31, v202
	v_readlane_b32 s39, v255, 15
	v_readlane_b32 s40, v253, 56
	v_readlane_b32 s41, v253, 57
	s_nop 1
	v_lshl_add_u64 v[202:203], v[202:203], 0, s[38:39]
	v_lshlrev_b64 v[202:203], 2, v[202:203]
	v_lshl_add_u64 v[204:205], s[40:41], 0, v[202:203]
	global_load_dword v250, v[204:205], off
	v_readlane_b32 s40, v253, 58
	v_readlane_b32 s41, v253, 59
	s_nop 1
	v_lshl_add_u64 v[202:203], s[40:41], 0, v[202:203]
	global_load_dword v251, v[202:203], off
; #define MFMA_BF(a, b, c) __builtin_amdgcn_mfma_f32_16x16x32_bf16(a, b, c, 0, 0, 0)
; __device__ __forceinline__ void rwkvA_phase(const Frame& F, int l) {
;     ...
;         {
;             f32x4 m[2] = {z4, z4}, n1[2] = {z4, z4}, n2[2] = {z4, z4}, ry[2] = {z4, z4}, y1[2] = {z4, z4}, y2[2] = {z4, z4};
; #pragma unroll
;             for (int ks = 0; ks < 2; ++ks) {
;                 const bf16x8 aPt = ch_trread(L + O_KB, tr, ks, qi, g), aVt = ch_trread(L + O_V, tr, ks, qi, g), aQt = ch_trread(L + O_AAK, tr, ks, qi, g);
;                 const bf16x8 aRb = ch_rowread(L + O_ARB, tr, ks, qi, g), aRk = ch_rowread(L + O_ARK, tr, ks, qi, g);
; #pragma unroll
;                 for (int t = 0; t < 2; ++t) {
;                     const bf16x8 bBh = ch_trread(L + O_BH, tcb + t, ks, qi, g), bKh = ch_trread(L + O_KH, tcb + t, ks, qi, g);
;                     const bf16x8 bP = ch_trread(L + O_KB, tcb + t, ks, qi, g), bV = ch_trread(L + O_V, tcb + t, ks, qi, g), bQ = ch_trread(L + O_AAK, tcb + t, ks, qi, g);
;                     m[t] = MFMA_BF(aPt, bBh, m[t]); n1[t] = MFMA_BF(aVt, bKh, n1[t]); n2[t] = MFMA_BF(aQt, bBh, n2[t]);
;                     ry[t] = MFMA_BF(aRb, bP, ry[t]); y1[t] = MFMA_BF(aRk, bV, y1[t]); y2[t] = MFMA_BF(aRb, bQ, y2[t]);
;                 }
;             }
.Lmy_pf_skip:
	ds_read_b64_tr_b16 v[4:5], v119 offset:55296
	ds_read_b64_tr_b16 v[6:7], v119 offset:55872
	ds_read_b64_tr_b16 v[8:9], v119 offset:36864
	ds_read_b64_tr_b16 v[12:13], v16 offset:18432
	ds_read_b64_tr_b16 v[14:15], v16 offset:19008
	ds_read_b64_tr_b16 v[10:11], v119 offset:37440
	ds_read_b64_tr_b16 v[18:19], v119 offset:64512
	ds_read_b64_tr_b16 v[20:21], v119 offset:65088
	ds_read_b64_tr_b16 v[22:23], v16 offset:27648
	ds_read_b64_tr_b16 v[24:25], v16 offset:28224
	ds_read_b128 v[48:51], v120
	s_waitcnt lgkmcnt(1)
	v_mfma_f32_16x16x32_bf16 v[172:175], v[8:11], v[22:25], v[0:3]
	ds_read_b64_tr_b16 v[22:23], v129 offset:55296
	ds_read_b64_tr_b16 v[24:25], v129 offset:55872
	v_mfma_f32_16x16x32_bf16 v[168:171], v[4:7], v[12:15], v[0:3]
	v_mfma_f32_16x16x32_bf16 v[32:35], v[18:21], v[12:15], v[0:3]
	ds_read_b128 v[52:55], v121
	ds_read_b64_tr_b16 v[12:13], v129 offset:36864
	s_waitcnt lgkmcnt(2)
	v_mfma_f32_16x16x32_bf16 v[36:39], v[48:51], v[22:25], v[0:3]
	ds_read_b64_tr_b16 v[14:15], v129 offset:37440
	ds_read_b64_tr_b16 v[22:23], v129 offset:64512
	ds_read_b64_tr_b16 v[24:25], v129 offset:65088
	s_waitcnt lgkmcnt(2)
	v_mfma_f32_16x16x32_bf16 v[40:43], v[52:55], v[12:15], v[0:3]
	s_waitcnt lgkmcnt(0)
	v_mfma_f32_16x16x32_bf16 v[44:47], v[48:51], v[22:25], v[0:3]
	ds_read_b64_tr_b16 v[12:13], v69 offset:18432
	ds_read_b64_tr_b16 v[14:15], v69 offset:19008
	ds_read_b64_tr_b16 v[22:23], v69 offset:27648
	ds_read_b64_tr_b16 v[24:25], v69 offset:28224
	s_waitcnt lgkmcnt(2)
	v_mfma_f32_16x16x32_bf16 v[28:31], v[4:7], v[12:15], v[0:3]
	s_waitcnt lgkmcnt(0)
	v_mfma_f32_16x16x32_bf16 v[4:7], v[8:11], v[22:25], v[0:3]
	ds_read_b64_tr_b16 v[22:23], v130 offset:55296
	v_mfma_f32_16x16x32_bf16 v[8:11], v[18:21], v[12:15], v[0:3]
	ds_read_b64_tr_b16 v[24:25], v130 offset:55872
	ds_read_b64_tr_b16 v[18:19], v130 offset:36864
	ds_read_b64_tr_b16 v[20:21], v130 offset:37440
	ds_read_b64_tr_b16 v[176:177], v130 offset:64512
	ds_read_b64_tr_b16 v[178:179], v130 offset:65088
	s_waitcnt lgkmcnt(4)
	v_mfma_f32_16x16x32_bf16 v[12:15], v[48:51], v[22:25], v[0:3]
	s_waitcnt lgkmcnt(2)
	v_mfma_f32_16x16x32_bf16 v[24:27], v[52:55], v[18:21], v[0:3]
	ds_read_b64_tr_b16 v[180:181], v119 offset:59904
	ds_read_b64_tr_b16 v[182:183], v119 offset:60480
	ds_read_b64_tr_b16 v[52:53], v119 offset:41472
	ds_read_b64_tr_b16 v[54:55], v119 offset:42048
	ds_read_b64_tr_b16 v[184:185], v16 offset:23040
	ds_read_b64_tr_b16 v[186:187], v16 offset:23616
	s_waitcnt lgkmcnt(6)
	v_mfma_f32_16x16x32_bf16 v[48:51], v[48:51], v[176:179], v[0:3]
	ds_read_b64_tr_b16 v[176:177], v122 offset:4608
	s_nop 1
	ds_read_b64_tr_b16 v[0:1], v16 offset:32256
	ds_read_b64_tr_b16 v[2:3], v16 offset:32832
	ds_read_b64_tr_b16 v[178:179], v122 offset:5184
	s_waitcnt lgkmcnt(4)
	v_mfma_f32_16x16x32_bf16 v[16:19], v[180:183], v[184:187], v[168:171]
	s_waitcnt lgkmcnt(1)
	v_mfma_f32_16x16x32_bf16 v[20:23], v[52:55], v[0:3], v[172:175]
	s_nop 0
	ds_read_b128 v[168:171], v120 offset:64
	ds_read_b64_tr_b16 v[0:1], v129 offset:59904
	ds_read_b64_tr_b16 v[2:3], v129 offset:60480
	s_waitcnt lgkmcnt(3)
	v_mfma_f32_16x16x32_bf16 v[32:35], v[176:179], v[184:187], v[32:35]
	ds_read_b128 v[172:175], v121 offset:64
	ds_read_b64_tr_b16 v[184:185], v129 offset:41472
	s_waitcnt lgkmcnt(2)
	v_mfma_f32_16x16x32_bf16 v[36:39], v[168:171], v[0:3], v[36:39]
	ds_read_b64_tr_b16 v[186:187], v129 offset:42048
	ds_read_b64_tr_b16 v[0:1], v123 offset:4608
	ds_read_b64_tr_b16 v[2:3], v123 offset:5184
	s_waitcnt lgkmcnt(2)
	v_mfma_f32_16x16x32_bf16 v[40:43], v[172:175], v[184:187], v[40:43]
	ds_read_b64_tr_b16 v[184:185], v69 offset:23040
	ds_read_b64_tr_b16 v[186:187], v69 offset:23616
	ds_read_b64_tr_b16 v[188:189], v69 offset:32256
	ds_read_b64_tr_b16 v[190:191], v69 offset:32832
	s_waitcnt lgkmcnt(4)
	v_mfma_f32_16x16x32_bf16 v[44:47], v[168:171], v[0:3], v[44:47]
	s_waitcnt lgkmcnt(2)
	v_mfma_f32_16x16x32_bf16 v[0:3], v[180:183], v[184:187], v[28:31]
	s_nop 2
	ds_read_b64_tr_b16 v[28:29], v130 offset:59904
	s_waitcnt lgkmcnt(1)
	v_mfma_f32_16x16x32_bf16 v[4:7], v[52:55], v[188:191], v[4:7]
	ds_read_b64_tr_b16 v[30:31], v130 offset:60480
	ds_read_b64_tr_b16 v[52:53], v130 offset:41472
	s_waitcnt lgkmcnt(1)
	v_mfma_f32_16x16x32_bf16 v[12:15], v[168:171], v[28:31], v[12:15]
	ds_read_b64_tr_b16 v[54:55], v130 offset:42048
	ds_read_b64_tr_b16 v[28:29], v124 offset:4608
	ds_read_b64_tr_b16 v[30:31], v124 offset:5184
	v_mfma_f32_16x16x32_bf16 v[8:11], v[176:179], v[184:187], v[8:11]
	s_waitcnt lgkmcnt(2)
	v_mfma_f32_16x16x32_bf16 v[24:27], v[172:175], v[52:55], v[24:27]
	v_mov_b32_e32 v55, 0
	v_mov_b32_e32 v54, 0
	s_waitcnt lgkmcnt(0)
; #define LAS __attribute__((address_space(3)))
; __device__ __forceinline__ unsigned cvt_pk_bf16(float lo, float hi) { return __builtin_bit_cast(unsigned, __builtin_convertvector((f32x2){lo, hi}, bf16x2n)); }
; __device__ __forceinline__ float bf2f(bf16_t h) { return __uint_as_float(((unsigned)h) << 16); }
; __device__ __forceinline__ void rwkvA_phase(const Frame& F, int l) {
;     ...
;             const int lo = (16 * tr + 4 * g) * 64 + 16 * tcb + qi;
;             float* Np = MN + (size_t)task * 2 * 4096 + 4096 + lo;
;             bf16_t* MTh = (bf16_t*)(MN + (size_t)task * 2 * 4096); bf16_t* MTl = MTh + 4096;
;             bf16_t* Rp = RY + (size_t)task * 4096 + lo;
;             const LAS bf16_t* Rt = (const LAS bf16_t*)(L + O_RT + (16 * tr + 4 * g) * CS + (16 * tcb + qi) * 2);
;             const int dstep = (dir == 0) ? AW : -AW;
;             float* Yp = (float*)(ws + WS_Y) + (size_t)dir * MROWS * AW + (size_t)scan_row(dir, c * 64 + 16 * tr + 4 * g) * AW + head * 64 + 16 * tcb + qi;
; #pragma unroll
;             for (int t = 0; t < 2; ++t) {
; #pragma unroll
;                 for (int jj = 0; jj < 4; ++jj) {
;                     const bool dg = (16 * tr + 4 * g + jj) == (16 * (tcb + t) + qi);
;                     m[t][jj] = (dg ? gL[16 * (tcb + t) + qi] : 0.f) - m[t][jj];
;                     Np[jj * 64 + t * 16] = n1[t][jj] - n2[t][jj];
;                     Rp[jj * 64 + t * 16] = f2bf(bf2f(Rt[jj * (CS / 2) + t * 16]) - ry[t][jj]);
;                     Yp[jj * dstep + t * 16] = y1[t][jj] - y2[t][jj];
;                 }
;                 float hi_[4];
; #pragma unroll
;                 for (int jj = 0; jj < 4; ++jj) hi_[jj] = bf2f(f2bf(m[t][jj]));
;                 u32x2 wh, wl; wh.x = cvt_pk_bf16(hi_[0], hi_[1]); wh.y = cvt_pk_bf16(hi_[2], hi_[3]);
;                 wl.x = cvt_pk_bf16(m[t][0] - hi_[0], m[t][1] - hi_[1]); wl.y = cvt_pk_bf16(m[t][2] - hi_[2], m[t][3] - hi_[3]);
;                 const int mo_ = (16 * (tcb + t) + qi) * 64 + 32 * (tr >> 1) + 8 * g + 4 * (tr & 1);
;                 *(u32x2*)(MTh + mo_) = wh; *(u32x2*)(MTl + mo_) = wl;
;             }
	v_mfma_f32_16x16x32_bf16 v[28:31], v[168:171], v[28:31], v[48:51]
	s_and_saveexec_b64 s[36:37], s[8:9]
	ds_read_b32 v54, v105
	s_or_b64 exec, exec, s[36:37]
	s_mul_i32 s3, s1, 0xffffff7c
	s_add_i32 s38, s3, s2
	s_ashr_i32 s3, s2, 31
	s_and_b32 s1, s1, 1
	s_lshl_b64 s[36:37], s[2:3], 15
	v_readlane_b32 s8, v255, 16
	s_add_u32 s70, s8, s36
	v_readlane_b32 s8, v255, 17
	s_addc_u32 s71, s8, s37
	s_lshl_b64 s[2:3], s[2:3], 13
	v_lshl_add_u64 v[48:49], v[60:61], 0, s[2:3]
	v_lshl_add_u32 v52, s38, 6, v77
	s_movk_i32 s2, 0x100
	v_cmp_gt_i32_e32 vcc, s2, v52
	s_cmp_eq_u32 s1, 0
	s_cselect_b64 s[68:69], -1, 0
	v_cndmask_b32_e32 v53, v226, v227, vcc
	v_add_u32_e32 v53, v53, v52
	v_sub_u32_e32 v52, 0x20ff, v52
	s_mul_i32 s1, s1, 0x2100000
	v_readlane_b32 s2, v255, 22
	v_cndmask_b32_e64 v52, v52, v53, s[68:69]
	s_add_u32 s2, s2, s1
	v_readlane_b32 s1, v255, 23
	v_ashrrev_i32_e32 v53, 31, v52
	s_addc_u32 s3, s1, 0
	v_lshlrev_b64 v[52:53], 12, v[52:53]
	v_sub_f32_e32 v20, v20, v32
	ds_read_u16 v32, v126 offset:9216
	v_lshl_add_u64 v[52:53], s[2:3], 0, v[52:53]
	s_ashr_i32 s1, s0, 31
	v_lshl_add_u64 v[50:51], v[58:59], 2, s[70:71]
	v_lshl_add_u64 v[52:53], s[0:1], 2, v[52:53]
	s_movk_i32 s0, 0x4000
	v_add_co_u32_e32 v130, vcc, s0, v50
	v_lshl_add_u64 v[52:53], v[52:53], 0, s[72:73]
	s_nop 0
	v_addc_co_u32_e32 v131, vcc, 0, v51, vcc
	flat_store_dword v[130:131], v20
	s_waitcnt lgkmcnt(0)
	v_lshlrev_b32_e32 v20, 16, v32
	v_sub_f32_e32 v20, v20, v36
	v_mov_b32_e32 v69, v128
	v_cvt_pk_bf16_f32 v20, v20, s0
	v_lshl_add_u64 v[52:53], v[52:53], 0, v[68:69]
	flat_store_short v[48:49], v20
	v_sub_f32_e32 v20, v40, v44
	flat_store_dword v[52:53], v20
	s_mov_b64 s[0:1], exec
	v_readlane_b32 s2, v255, 26
	v_readlane_b32 s3, v255, 27
	s_and_b64 s[2:3], s[0:1], s[2:3]
	s_mov_b64 exec, s[2:3]
	ds_read_b32 v55, v105
	s_or_b64 exec, exec, s[0:1]
	s_mov_b64 s[0:1], 0x4000
	v_lshl_add_u64 v[50:51], v[50:51], 0, s[0:1]
	v_sub_f32_e32 v20, v21, v33
	flat_store_dword v[50:51], v20 offset:256
	ds_read_u16 v20, v126 offset:9360
	v_readlane_b32 s8, v255, 28
	v_mov_b32_e32 v36, 0
	v_readlane_b32 s9, v255, 29
	s_waitcnt lgkmcnt(0)
	v_lshlrev_b32_e32 v20, 16, v20
	v_sub_f32_e32 v20, v20, v37
	v_cvt_pk_bf16_f32 v20, v20, s0
	s_and_b64 s[0:1], s[68:69], exec
	s_movk_i32 s0, 0xfc00
	s_cselect_b32 s1, 0, -1
	s_cselect_b32 s0, 0x400, s0
	flat_store_short v[48:49], v20 offset:128
	v_sub_f32_e32 v20, v41, v45
	v_lshl_add_u64 v[32:33], s[0:1], 2, v[52:53]
	v_mov_b32_e32 v37, 0
	flat_store_dword v[32:33], v20
	s_and_saveexec_b64 s[2:3], s[8:9]
	ds_read_b32 v37, v105
	s_or_b64 exec, exec, s[2:3]
	v_sub_f32_e32 v20, v22, v34
	flat_store_dword v[50:51], v20 offset:512
	ds_read_u16 v20, v126 offset:9504
	s_lshl_b64 s[2:3], s[0:1], 2
	v_readlane_b32 s8, v255, 30
	v_sub_f32_e32 v22, v42, v46
	v_readlane_b32 s9, v255, 31
	s_waitcnt lgkmcnt(0)
	v_lshlrev_b32_e32 v20, 16, v20
	v_sub_f32_e32 v20, v20, v38
	v_cvt_pk_bf16_f32 v20, v20, s0
	flat_store_short v[48:49], v20 offset:256
	v_lshl_add_u64 v[20:21], v[32:33], 0, s[2:3]
	flat_store_dword v[20:21], v22
	s_and_saveexec_b64 s[0:1], s[8:9]
	ds_read_b32 v36, v105
	s_or_b64 exec, exec, s[0:1]
	v_sub_f32_e32 v40, v54, v16
	ds_read_u16 v16, v126 offset:9648
	s_add_u32 s0, s70, 0x2000
	v_sub_f32_e32 v41, v55, v17
	v_sub_f32_e32 v17, v23, v35
	flat_store_dword v[50:51], v17 offset:768
	s_waitcnt lgkmcnt(0)
	v_lshlrev_b32_e32 v16, 16, v16
	v_sub_f32_e32 v16, v16, v39
	v_cvt_pk_bf16_f32 v16, v16, s0
	flat_store_short v[48:49], v16 offset:384
	v_sub_f32_e32 v22, v43, v47
	v_lshl_add_u64 v[16:17], v[20:21], 0, s[2:3]
	flat_store_dword v[16:17], v22
	v_cvt_pk_bf16_f32 v22, v40, v41
	v_and_b32_e32 v23, 0xffff0000, v22
	v_lshlrev_b32_e32 v22, 16, v22
	v_sub_f32_e32 v18, v37, v18
	v_sub_f32_e32 v19, v36, v19
	v_cvt_pk_bf16_f32 v34, v22, v23
	v_pk_add_f32 v[22:23], v[40:41], v[22:23] neg_lo:[0,1] neg_hi:[0,1]
	s_addc_u32 s1, s71, 0
	v_cvt_pk_bf16_f32 v22, v22, v23
	v_cvt_pk_bf16_f32 v23, v18, v19
	v_and_b32_e32 v37, 0xffff0000, v23
	v_lshlrev_b32_e32 v36, 16, v23
	v_pk_add_f32 v[18:19], v[18:19], v[36:37] neg_lo:[0,1] neg_hi:[0,1]
	v_cvt_pk_bf16_f32 v35, v36, v37
	v_cvt_pk_bf16_f32 v23, v18, v19
	v_lshl_add_u64 v[18:19], s[70:71], 0, v[70:71]
	flat_store_dwordx2 v[18:19], v[34:35]
	v_lshl_add_u64 v[18:19], s[0:1], 0, v[70:71]
	v_readlane_b32 s8, v255, 32
	flat_store_dwordx2 v[18:19], v[22:23]
	v_mov_b32_e32 v19, 0
	v_mov_b32_e32 v18, 0
	v_readlane_b32 s9, v255, 33
	s_and_saveexec_b64 s[2:3], s[8:9]
	ds_read_b32 v18, v107
	s_or_b64 exec, exec, s[2:3]
	v_sub_f32_e32 v4, v4, v8
	flat_store_dword v[50:51], v4 offset:64
	ds_read_u16 v4, v126 offset:9248
	v_readlane_b32 s8, v255, 51
	v_readlane_b32 s9, v255, 52
	s_waitcnt lgkmcnt(0)
	v_lshlrev_b32_e32 v4, 16, v4
	v_sub_f32_e32 v4, v4, v12
	v_cvt_pk_bf16_f32 v4, v4, s0
	flat_store_short v[48:49], v4 offset:32
	v_sub_f32_e32 v4, v24, v28
	flat_store_dword v[52:53], v4 offset:64
	s_and_saveexec_b64 s[2:3], s[8:9]
	ds_read_b32 v19, v107
	s_or_b64 exec, exec, s[2:3]
	v_sub_f32_e32 v4, v5, v9
	flat_store_dword v[50:51], v4 offset:320
	ds_read_u16 v4, v126 offset:9392
	v_readlane_b32 s8, v255, 53
	v_mov_b32_e32 v5, 0
	v_readlane_b32 s9, v255, 54
	s_waitcnt lgkmcnt(0)
	v_lshlrev_b32_e32 v4, 16, v4
	v_sub_f32_e32 v4, v4, v13
	v_cvt_pk_bf16_f32 v4, v4, s0
	flat_store_short v[48:49], v4 offset:160
	v_sub_f32_e32 v4, v25, v29
	flat_store_dword v[32:33], v4 offset:64
	v_mov_b32_e32 v4, 0
	s_and_saveexec_b64 s[2:3], s[8:9]
	ds_read_b32 v5, v107
	s_or_b64 exec, exec, s[2:3]
	v_sub_f32_e32 v6, v6, v10
	flat_store_dword v[50:51], v6 offset:576
	ds_read_u16 v6, v126 offset:9536
	v_readlane_b32 s8, v255, 55
	v_readlane_b32 s9, v255, 56
	s_waitcnt lgkmcnt(0)
	v_lshlrev_b32_e32 v6, 16, v6
	v_sub_f32_e32 v6, v6, v14
	v_cvt_pk_bf16_f32 v6, v6, s0
	flat_store_short v[48:49], v6 offset:288
	v_sub_f32_e32 v6, v26, v30
	flat_store_dword v[20:21], v6 offset:64
	s_and_saveexec_b64 s[2:3], s[8:9]
	s_cbranch_execz .LBB0_749
	ds_read_b32 v4, v107
	s_branch .LBB0_749
